# attention PV: one counted lgkmcnt wait per two MFMAs; O rescale skipped on each item's first tile (O is zero)
# baseline (speedup 1.0000x reference)
.Lat_y_nomask_b:
	v_max3_f32 v247, v66, v67, v68
	v_max3_f32 v0, v82, v83, v84
	v_max3_f32 v247, v247, v69, v70
	v_max3_f32 v0, v0, v85, v86
	v_max3_f32 v247, v247, v71, v72
	v_max3_f32 v0, v0, v87, v88
	v_max3_f32 v247, v247, v73, v74
	v_max3_f32 v0, v0, v89, v90
	v_max3_f32 v247, v247, v75, v76
	v_max3_f32 v0, v0, v91, v92
	v_max3_f32 v247, v247, v77, v78
	v_max3_f32 v0, v0, v93, v94
	v_max3_f32 v247, v247, v79, v80
	v_max3_f32 v0, v0, v95, v96
	v_max3_f32 v247, v247, v81, v97
	v_max_f32_e32 v247, v247, v0
	v_mov_b32_e32 v0, v247
	s_nop 1
	v_permlane32_swap_b32_e32 v0, v247
	s_nop 1
	v_max_f32_e32 v247, v247, v0
	v_mul_f32_e32 v0, v235, v247
	v_sub_f32_e32 v243, v0, v236
	v_cmp_lt_f32_e32 vcc, 0x41000000, v243
	s_nop 1
	v_cndmask_b32_e32 v244, v236, v0, vcc
	v_sub_f32_e32 v248, v236, v244
	v_exp_f32_e32 v248, v248
	s_nop 0
	s_cmp_eq_u32 s96, 0
	s_cbranch_scc1 .Lat_y_norescale_b
	s_cbranch_vccz .Lat_y_norescale_b
	v_pk_mul_f32 v[2:3], v[2:3], v[248:249] op_sel_hi:[1,0]
	v_pk_mul_f32 v[4:5], v[4:5], v[248:249] op_sel_hi:[1,0]
	v_pk_mul_f32 v[6:7], v[6:7], v[248:249] op_sel_hi:[1,0]
	v_pk_mul_f32 v[8:9], v[8:9], v[248:249] op_sel_hi:[1,0]
	v_pk_mul_f32 v[10:11], v[10:11], v[248:249] op_sel_hi:[1,0]
	v_pk_mul_f32 v[12:13], v[12:13], v[248:249] op_sel_hi:[1,0]
	v_pk_mul_f32 v[14:15], v[14:15], v[248:249] op_sel_hi:[1,0]
	v_pk_mul_f32 v[16:17], v[16:17], v[248:249] op_sel_hi:[1,0]
	v_pk_mul_f32 v[18:19], v[18:19], v[248:249] op_sel_hi:[1,0]
	v_pk_mul_f32 v[20:21], v[20:21], v[248:249] op_sel_hi:[1,0]
	v_pk_mul_f32 v[22:23], v[22:23], v[248:249] op_sel_hi:[1,0]
	v_pk_mul_f32 v[24:25], v[24:25], v[248:249] op_sel_hi:[1,0]
	v_pk_mul_f32 v[26:27], v[26:27], v[248:249] op_sel_hi:[1,0]
	v_pk_mul_f32 v[28:29], v[28:29], v[248:249] op_sel_hi:[1,0]
	v_pk_mul_f32 v[30:31], v[30:31], v[248:249] op_sel_hi:[1,0]
	v_pk_mul_f32 v[32:33], v[32:33], v[248:249] op_sel_hi:[1,0]
	v_pk_mul_f32 v[34:35], v[34:35], v[248:249] op_sel_hi:[1,0]
	v_pk_mul_f32 v[36:37], v[36:37], v[248:249] op_sel_hi:[1,0]
	v_pk_mul_f32 v[38:39], v[38:39], v[248:249] op_sel_hi:[1,0]
	v_pk_mul_f32 v[40:41], v[40:41], v[248:249] op_sel_hi:[1,0]
	v_pk_mul_f32 v[42:43], v[42:43], v[248:249] op_sel_hi:[1,0]
	v_pk_mul_f32 v[44:45], v[44:45], v[248:249] op_sel_hi:[1,0]
	v_pk_mul_f32 v[46:47], v[46:47], v[248:249] op_sel_hi:[1,0]
	v_pk_mul_f32 v[48:49], v[48:49], v[248:249] op_sel_hi:[1,0]
	v_pk_mul_f32 v[50:51], v[50:51], v[248:249] op_sel_hi:[1,0]
	v_pk_mul_f32 v[52:53], v[52:53], v[248:249] op_sel_hi:[1,0]
	v_pk_mul_f32 v[54:55], v[54:55], v[248:249] op_sel_hi:[1,0]
	v_pk_mul_f32 v[56:57], v[56:57], v[248:249] op_sel_hi:[1,0]
	v_pk_mul_f32 v[58:59], v[58:59], v[248:249] op_sel_hi:[1,0]
	v_pk_mul_f32 v[60:61], v[60:61], v[248:249] op_sel_hi:[1,0]
	v_pk_mul_f32 v[62:63], v[62:63], v[248:249] op_sel_hi:[1,0]
	v_pk_mul_f32 v[64:65], v[64:65], v[248:249] op_sel_hi:[1,0]

.Lat_x_pvb:
	s_mul_i32 s37, s72, 0x4400
	v_add_u32_e32 v243, s37, v231
	v_add_u32_e32 v244, 0x1100, v243
	v_add_u32_e32 v245, 0x2200, v243
	v_add_u32_e32 v246, 0x3300, v243
	ds_read2_b64 v[82:85], v243 offset0:0 offset1:2
	ds_read2_b64 v[86:89], v244 offset0:0 offset1:2
	ds_read2_b64 v[90:93], v245 offset0:0 offset1:2
	s_waitcnt lgkmcnt(1)
	v_mfma_f32_32x32x16_bf16 v[2:17], v[82:85], v[66:69], v[2:17]
	ds_read2_b64 v[94:97], v246 offset0:0 offset1:2
	v_mfma_f32_32x32x16_bf16 v[18:33], v[86:89], v[66:69], v[18:33]
	ds_read2_b64 v[82:85], v243 offset0:4 offset1:6
	s_waitcnt lgkmcnt(1)
	v_mfma_f32_32x32x16_bf16 v[34:49], v[90:93], v[66:69], v[34:49]
	ds_read2_b64 v[86:89], v244 offset0:4 offset1:6
	v_mfma_f32_32x32x16_bf16 v[50:65], v[94:97], v[66:69], v[50:65]
	ds_read2_b64 v[90:93], v245 offset0:4 offset1:6
	s_waitcnt lgkmcnt(1)
	v_mfma_f32_32x32x16_bf16 v[2:17], v[82:85], v[70:73], v[2:17]
	ds_read2_b64 v[94:97], v246 offset0:4 offset1:6
	v_mfma_f32_32x32x16_bf16 v[18:33], v[86:89], v[70:73], v[18:33]
	ds_read2_b64 v[82:85], v243 offset0:8 offset1:10
	s_waitcnt lgkmcnt(1)
	v_mfma_f32_32x32x16_bf16 v[34:49], v[90:93], v[70:73], v[34:49]
	ds_read2_b64 v[86:89], v244 offset0:8 offset1:10
	v_mfma_f32_32x32x16_bf16 v[50:65], v[94:97], v[70:73], v[50:65]
	ds_read2_b64 v[90:93], v245 offset0:8 offset1:10
	s_waitcnt lgkmcnt(1)
	v_mfma_f32_32x32x16_bf16 v[2:17], v[82:85], v[74:77], v[2:17]
	ds_read2_b64 v[94:97], v246 offset0:8 offset1:10
	v_mfma_f32_32x32x16_bf16 v[18:33], v[86:89], v[74:77], v[18:33]
	ds_read2_b64 v[82:85], v243 offset0:12 offset1:14
	s_waitcnt lgkmcnt(1)
	v_mfma_f32_32x32x16_bf16 v[34:49], v[90:93], v[74:77], v[34:49]
	ds_read2_b64 v[86:89], v244 offset0:12 offset1:14
	v_mfma_f32_32x32x16_bf16 v[50:65], v[94:97], v[74:77], v[50:65]
	ds_read2_b64 v[90:93], v245 offset0:12 offset1:14
	s_waitcnt lgkmcnt(1)
	v_mfma_f32_32x32x16_bf16 v[2:17], v[82:85], v[78:81], v[2:17]
	ds_read2_b64 v[94:97], v246 offset0:12 offset1:14
	v_mfma_f32_32x32x16_bf16 v[18:33], v[86:89], v[78:81], v[18:33]
	s_waitcnt lgkmcnt(0)
	v_mfma_f32_32x32x16_bf16 v[34:49], v[90:93], v[78:81], v[34:49]
	v_mfma_f32_32x32x16_bf16 v[50:65], v[94:97], v[78:81], v[50:65]
